# mixer-A: LDS-DMA issue moved from tile head into the QK1 nop slot; prio 1 waves 4-7
# speedup vs baseline: 1.0132x; 1.0132x over previous
.LBB0_407:
	v_mbcnt_lo_u32_b32 v128, -1, 0
	v_mbcnt_hi_u32_b32 v128, -1, v128
	s_add_i32 s7, s7, 0
	v_bfe_u32 v129, v128, 2, 2
	v_lshrrev_b32_e32 v130, 3, v128
	v_bfe_u32 v132, v128, 1, 1
	v_and_or_b32 v131, v130, s64, v129
	v_and_or_b32 v130, v130, 2, v132
	v_lshlrev_b32_e32 v128, 3, v128
	v_lshlrev_b32_e32 v131, 8, v131
	v_lshlrev_b32_e32 v130, 4, v130
	v_and_b32_e32 v128, 8, v128
	v_or3_b32 v160, v130, v131, v128
	v_lshlrev_b32_e32 v162, 6, v129
	v_mbcnt_lo_u32_b32 v128, -1, 0
	v_mbcnt_hi_u32_b32 v128, -1, v128
	v_or_b32_e32 v163, v160, v162
	v_ashrrev_i32_e32 v129, 5, v128
	v_lshlrev_b32_e32 v130, 7, v128
	v_lshrrev_b32_e32 v133, 1, v128
	v_and_b32_e32 v132, 0xf80, v130
	v_bitop3_b32 v128, v133, v129, 7 bitop3:0x6c
	v_lshl_add_u32 v134, v128, 4, v132
	v_add_u32_e32 v128, 2, v129
	v_bitop3_b32 v128, v128, v133, 7 bitop3:0x78
	v_lshl_add_u32 v136, v128, 4, v132
	v_add_u32_e32 v128, 4, v129
	v_bitop3_b32 v128, v128, v133, 7 bitop3:0x78
	v_add_u32_e32 v207, s7, v134
	v_lshl_add_u32 v168, v128, 4, v132
	v_add_u32_e32 v135, 6, v129
	ds_read_b128 v[128:131], v207
	v_bitop3_b32 v133, v135, v133, 7 bitop3:0x78
	v_add_u32_e32 v224, s48, v134
	v_add_u32_e32 v225, s7, v136
	v_lshl_add_u32 v169, v133, 4, v132
	ds_read_b128 v[132:135], v224
	v_add_u32_e32 v226, s48, v136
	ds_read_b128 v[136:139], v225
	ds_read_b128 v[140:143], v226
	v_bitop3_b32 v203, v160, s37, v162 bitop3:0x36
	v_bitop3_b32 v206, v160, s41, v162 bitop3:0x36
	s_waitcnt lgkmcnt(2)
	v_mfma_f32_32x32x16_bf16 v[144:159], v[128:131], v[132:135], 0
	v_add_u32_e32 v227, s7, v168
	v_add_u32_e32 v228, s48, v168
	ds_read_b128 v[128:131], v227
	ds_read_b128 v[132:135], v228
	s_waitcnt lgkmcnt(2)
	v_mfma_f32_32x32x16_bf16 v[144:159], v[136:139], v[140:143], v[144:159]
	v_add_u32_e32 v230, s7, v169
	v_add_u32_e32 v232, s48, v169
	ds_read_b128 v[136:139], v230
	ds_read_b128 v[140:143], v232
	s_waitcnt lgkmcnt(2)
	v_mfma_f32_32x32x16_bf16 v[144:159], v[128:131], v[132:135], v[144:159]
	ds_read_b128 v[128:131], v207 offset:8192
	ds_read_b128 v[132:135], v224 offset:4096
	s_waitcnt lgkmcnt(2)
	v_mfma_f32_32x32x16_bf16 v[144:159], v[136:139], v[140:143], v[144:159]
	ds_read_b128 v[178:181], v225 offset:8192
	ds_read_b128 v[182:185], v226 offset:4096
	s_waitcnt lgkmcnt(2)
	v_mfma_f32_32x32x16_bf16 v[128:143], v[128:131], v[132:135], 0
	s_nop 7
	v_exp_f32_e32 v173, v144
	v_exp_f32_e32 v169, v145
	v_exp_f32_e32 v177, v146
	v_exp_f32_e32 v171, v147
	ds_read_b128 v[144:147], v227 offset:8192
	ds_read_b128 v[190:193], v228 offset:4096
	s_waitcnt lgkmcnt(2)
	v_mfma_f32_32x32x16_bf16 v[128:143], v[178:181], v[182:185], v[128:143]
	v_exp_f32_e32 v183, v148
	v_exp_f32_e32 v175, v149
	v_exp_f32_e32 v189, v150
	v_exp_f32_e32 v179, v151
	ds_read_b128 v[148:151], v230 offset:8192
	ds_read_b128 v[196:199], v232 offset:4096
	s_waitcnt lgkmcnt(2)
	v_mfma_f32_32x32x16_bf16 v[128:143], v[144:147], v[190:193], v[128:143]
	v_exp_f32_e32 v193, v152
	v_exp_f32_e32 v181, v153
	v_exp_f32_e32 v195, v154
	v_exp_f32_e32 v187, v155
	s_waitcnt lgkmcnt(0)
	v_mfma_f32_32x32x16_bf16 v[128:143], v[148:151], v[196:199], v[128:143]
	v_exp_f32_e32 v197, v156
	v_exp_f32_e32 v185, v157
	v_exp_f32_e32 v199, v158
	v_exp_f32_e32 v191, v159
	s_cmp_eq_u32 s4, 0x3f0000
	s_cbranch_scc1 .Lattn_nodma_a
	v_mov_b32_e32 v213, 0
	v_add_u32_e32 v212, s4, v202
	s_xor_b32 s8, s7, 0x4000
	v_lshl_add_u64 v[208:209], v[212:213], 1, s[66:67]
	s_add_i32 s9, s49, s8
	s_mov_b32 s10, m0
	s_mov_b32 m0, s9
	s_nop 0
	global_load_lds_dwordx4 v[208:209], off
	s_mov_b32 m0, s10
	v_add_u32_e32 v210, s4, v201
	v_lshl_add_u64 v[208:209], v[208:209], 0, s[38:39]
	s_add_i32 s9, s33, s8
	s_mov_b32 s10, m0
	s_mov_b32 m0, s9
	s_nop 0
	global_load_lds_dwordx4 v[208:209], off
	s_mov_b32 m0, s10
	v_add_u32_e32 v212, 0x10000, v210
	v_lshl_add_u64 v[208:209], v[212:213], 1, s[68:69]
	s_add_i32 s9, s54, s8
	s_mov_b32 s10, m0
	s_mov_b32 m0, s9
	s_nop 0
	global_load_lds_dwordx4 v[208:209], off
	s_mov_b32 m0, s10
	v_add_u32_e32 v212, 0x18000, v210
	v_lshl_add_u64 v[208:209], v[212:213], 1, s[68:69]
	s_add_i32 s8, s47, s8
	s_mov_b32 s9, m0
	s_mov_b32 m0, s8
	s_nop 0
	global_load_lds_dwordx4 v[208:209], off
	s_mov_b32 m0, s9
	s_branch .Lattn_dma_done_a
.Lattn_nodma_a:
	s_nop 7
.Lattn_dma_done_a:
	v_exp_f32_e32 v172, v128
	v_exp_f32_e32 v170, v129
	v_exp_f32_e32 v176, v130
	v_exp_f32_e32 v168, v131
	v_exp_f32_e32 v182, v132
	v_exp_f32_e32 v178, v133
	v_exp_f32_e32 v188, v134
	v_exp_f32_e32 v174, v135
	v_exp_f32_e32 v192, v136
	v_exp_f32_e32 v186, v137
	v_exp_f32_e32 v194, v138
	v_exp_f32_e32 v180, v139
	v_exp_f32_e32 v196, v140
	v_exp_f32_e32 v190, v141
	v_exp_f32_e32 v198, v142
	v_exp_f32_e32 v184, v143
	v_cvt_pk_bf16_f32 v144, v173, v169
	v_cvt_pk_bf16_f32 v145, v177, v171
	v_cvt_pk_bf16_f32 v146, v183, v175
	v_cvt_pk_bf16_f32 v147, v189, v179
	v_cvt_pk_bf16_f32 v148, v193, v181
	v_cvt_pk_bf16_f32 v149, v195, v187
	v_cvt_pk_bf16_f32 v150, v197, v185
	v_cvt_pk_bf16_f32 v151, v199, v191
	v_cvt_pk_bf16_f32 v128, v172, v170
	v_cvt_pk_bf16_f32 v129, v176, v168
	v_cvt_pk_bf16_f32 v130, v182, v178
	v_cvt_pk_bf16_f32 v131, v188, v174
	v_cvt_pk_bf16_f32 v132, v192, v186
	v_cvt_pk_bf16_f32 v133, v194, v180
	v_cvt_pk_bf16_f32 v134, v196, v190
	v_cvt_pk_bf16_f32 v135, v198, v184
	v_add3_u32 v160, s7, v162, v160
	v_xad_u32 v252, v163, 64, s7
	v_add_u32_e32 v203, s7, v203
	v_add_u32_e32 v205, s7, v206
	ds_read_b64_tr_b16 v[136:137], v160 offset:32768
	ds_read_b64_tr_b16 v[138:139], v160 offset:34816
	ds_read_b64_tr_b16 v[140:141], v160 offset:36864
	ds_read_b64_tr_b16 v[142:143], v160 offset:38912
	ds_read_b64_tr_b16 v[152:153], v252 offset:32768
	ds_read_b64_tr_b16 v[154:155], v252 offset:34816
	ds_read_b64_tr_b16 v[156:157], v252 offset:36864
	ds_read_b64_tr_b16 v[158:159], v252 offset:38912
	ds_read_b64_tr_b16 v[208:209], v203 offset:32768
	ds_read_b64_tr_b16 v[210:211], v203 offset:34816
	ds_read_b64_tr_b16 v[212:213], v203 offset:36864
	ds_read_b64_tr_b16 v[214:215], v203 offset:38912
	ds_read_b64_tr_b16 v[216:217], v205 offset:32768
	ds_read_b64_tr_b16 v[218:219], v205 offset:34816
	ds_read_b64_tr_b16 v[220:221], v205 offset:36864
	ds_read_b64_tr_b16 v[222:223], v205 offset:38912
	s_waitcnt lgkmcnt(14)
	v_mfma_f32_32x32x16_bf16 v[64:79], v[144:147], v[136:139], v[64:79]
	v_mfma_f32_32x32x16_bf16 v[0:15], v[128:131], v[136:139], v[0:15]
	s_waitcnt lgkmcnt(10)
	v_mfma_f32_32x32x16_bf16 v[80:95], v[144:147], v[152:155], v[80:95]
	v_mfma_f32_32x32x16_bf16 v[16:31], v[128:131], v[152:155], v[16:31]
	s_waitcnt lgkmcnt(6)
	v_mfma_f32_32x32x16_bf16 v[96:111], v[144:147], v[208:211], v[96:111]
	v_mfma_f32_32x32x16_bf16 v[32:47], v[128:131], v[208:211], v[32:47]
	s_waitcnt lgkmcnt(2)
	v_mfma_f32_32x32x16_bf16 v[112:127], v[144:147], v[216:219], v[112:127]
	v_mfma_f32_32x32x16_bf16 v[48:63], v[128:131], v[216:219], v[48:63]
	v_mfma_f32_32x32x16_bf16 v[64:79], v[148:151], v[140:143], v[64:79]
	v_mfma_f32_32x32x16_bf16 v[0:15], v[132:135], v[140:143], v[0:15]
	v_mfma_f32_32x32x16_bf16 v[80:95], v[148:151], v[156:159], v[80:95]
	v_mfma_f32_32x32x16_bf16 v[16:31], v[132:135], v[156:159], v[16:31]
	v_mfma_f32_32x32x16_bf16 v[96:111], v[148:151], v[212:215], v[96:111]
	v_mfma_f32_32x32x16_bf16 v[32:47], v[132:135], v[212:215], v[32:47]
	s_waitcnt lgkmcnt(0)
	v_mfma_f32_32x32x16_bf16 v[112:127], v[148:151], v[220:223], v[112:127]
	v_mfma_f32_32x32x16_bf16 v[48:63], v[132:135], v[220:223], v[48:63]
	ds_read_b128 v[128:131], v207 offset:4096
	ds_read_b128 v[132:135], v224
	ds_read_b128 v[136:139], v225 offset:4096
	ds_read_b128 v[140:143], v226
	s_waitcnt lgkmcnt(2)
	v_mfma_f32_32x32x16_bf16 v[144:159], v[128:131], v[132:135], 0
	ds_read_b128 v[128:131], v227 offset:4096
	ds_read_b128 v[132:135], v228
	s_waitcnt lgkmcnt(2)
	v_mfma_f32_32x32x16_bf16 v[144:159], v[136:139], v[140:143], v[144:159]
	ds_read_b128 v[136:139], v230 offset:4096
	ds_read_b128 v[140:143], v232
	s_waitcnt lgkmcnt(2)
	v_mfma_f32_32x32x16_bf16 v[144:159], v[128:131], v[132:135], v[144:159]
	ds_read_b128 v[128:131], v207 offset:12288
	ds_read_b128 v[132:135], v224 offset:4096
	s_waitcnt lgkmcnt(2)
	v_mfma_f32_32x32x16_bf16 v[144:159], v[136:139], v[140:143], v[144:159]
	ds_read_b128 v[208:211], v225 offset:12288
	ds_read_b128 v[212:215], v226 offset:4096
	s_waitcnt lgkmcnt(2)
	v_mfma_f32_32x32x16_bf16 v[128:143], v[128:131], v[132:135], 0
	s_nop 7
	v_exp_f32_e32 v229, v144
	v_exp_f32_e32 v145, v145
	v_exp_f32_e32 v231, v146
	v_exp_f32_e32 v147, v147
	ds_read_b128 v[216:219], v227 offset:12288
	ds_read_b128 v[220:223], v228 offset:4096
	s_waitcnt lgkmcnt(2)
	v_mfma_f32_32x32x16_bf16 v[128:143], v[208:211], v[212:215], v[128:143]
	v_exp_f32_e32 v233, v148
	v_exp_f32_e32 v235, v149
	v_exp_f32_e32 v237, v150
	v_exp_f32_e32 v239, v151
	ds_read_b128 v[148:151], v230 offset:12288
	ds_read_b128 v[208:211], v232 offset:4096
	s_waitcnt lgkmcnt(2)
	v_mfma_f32_32x32x16_bf16 v[128:143], v[216:219], v[220:223], v[128:143]
	v_exp_f32_e32 v241, v152
	v_exp_f32_e32 v243, v153
	v_exp_f32_e32 v245, v154
	v_exp_f32_e32 v247, v155
	s_waitcnt lgkmcnt(0)
	v_mfma_f32_32x32x16_bf16 v[128:143], v[148:151], v[208:211], v[128:143]
	v_exp_f32_e32 v249, v156
	v_exp_f32_e32 v251, v157
	v_exp_f32_e32 v207, v158
	v_exp_f32_e32 v163, v159
	s_nop 7
	v_exp_f32_e32 v228, v128
	v_exp_f32_e32 v146, v129
	v_exp_f32_e32 v230, v130
	v_exp_f32_e32 v144, v131
	v_exp_f32_e32 v232, v132
	v_exp_f32_e32 v238, v133
	v_exp_f32_e32 v236, v134
	v_exp_f32_e32 v234, v135
	v_exp_f32_e32 v240, v136
	v_exp_f32_e32 v246, v137
	v_exp_f32_e32 v244, v138
	v_exp_f32_e32 v242, v139
	v_exp_f32_e32 v248, v140
	v_exp_f32_e32 v162, v141
	v_exp_f32_e32 v206, v142
	v_exp_f32_e32 v250, v143
	v_cvt_pk_bf16_f32 v148, v229, v145
	v_cvt_pk_bf16_f32 v149, v231, v147
	v_cvt_pk_bf16_f32 v150, v233, v235
	v_cvt_pk_bf16_f32 v151, v237, v239
	v_cvt_pk_bf16_f32 v152, v241, v243
	v_cvt_pk_bf16_f32 v153, v245, v247
	v_cvt_pk_bf16_f32 v154, v249, v251
	v_cvt_pk_bf16_f32 v155, v207, v163
	v_cvt_pk_bf16_f32 v128, v228, v146
	v_cvt_pk_bf16_f32 v129, v230, v144
	v_cvt_pk_bf16_f32 v130, v232, v238
	v_cvt_pk_bf16_f32 v131, v236, v234
	v_cvt_pk_bf16_f32 v132, v240, v246
	v_cvt_pk_bf16_f32 v133, v244, v242
	v_cvt_pk_bf16_f32 v134, v248, v162
	v_cvt_pk_bf16_f32 v135, v206, v250
	ds_read_b64_tr_b16 v[136:137], v160 offset:40960
	ds_read_b64_tr_b16 v[138:139], v160 offset:43008
	ds_read_b64_tr_b16 v[140:141], v160 offset:45056
	ds_read_b64_tr_b16 v[142:143], v160 offset:47104
	ds_read_b64_tr_b16 v[156:157], v252 offset:40960
	ds_read_b64_tr_b16 v[158:159], v252 offset:43008
	ds_read_b64_tr_b16 v[208:209], v252 offset:45056
	ds_read_b64_tr_b16 v[210:211], v252 offset:47104
	ds_read_b64_tr_b16 v[212:213], v203 offset:40960
	ds_read_b64_tr_b16 v[214:215], v203 offset:43008
	ds_read_b64_tr_b16 v[216:217], v203 offset:45056
	ds_read_b64_tr_b16 v[218:219], v203 offset:47104
	ds_read_b64_tr_b16 v[220:221], v205 offset:40960
	ds_read_b64_tr_b16 v[222:223], v205 offset:43008
	ds_read_b64_tr_b16 v[224:225], v205 offset:45056
	ds_read_b64_tr_b16 v[226:227], v205 offset:47104
	s_waitcnt lgkmcnt(14)
	v_mfma_f32_32x32x16_bf16 v[64:79], v[148:151], v[136:139], v[64:79]
	v_mfma_f32_32x32x16_bf16 v[0:15], v[128:131], v[136:139], v[0:15]
	s_waitcnt lgkmcnt(10)
	v_mfma_f32_32x32x16_bf16 v[80:95], v[148:151], v[156:159], v[80:95]
	v_mfma_f32_32x32x16_bf16 v[16:31], v[128:131], v[156:159], v[16:31]
	s_waitcnt lgkmcnt(6)
	v_mfma_f32_32x32x16_bf16 v[96:111], v[148:151], v[212:215], v[96:111]
	v_mfma_f32_32x32x16_bf16 v[32:47], v[128:131], v[212:215], v[32:47]
	s_waitcnt lgkmcnt(2)
	v_mfma_f32_32x32x16_bf16 v[112:127], v[148:151], v[220:223], v[112:127]
	v_mfma_f32_32x32x16_bf16 v[48:63], v[128:131], v[220:223], v[48:63]
	v_add_f32_e64 v128, v172, v176
	v_add_f32_e64 v129, v173, v177
	v_add_f32_e64 v130, v168, v170
	v_add_f32_e64 v131, v169, v171
	v_add_f32_e64 v128, v128, 0
	v_add_f32_e64 v129, v129, 0
	v_pk_add_f32 v[136:137], v[182:183], v[188:189]
	v_pk_add_f32 v[130:131], v[130:131], 0 op_sel_hi:[1,0]
	v_pk_add_f32 v[128:129], v[136:137], v[128:129]
	v_pk_add_f32 v[136:137], v[174:175], v[178:179]
	v_pk_add_f32 v[138:139], v[232:233], v[236:237]
	v_pk_add_f32 v[130:131], v[136:137], v[130:131]
	v_pk_add_f32 v[136:137], v[192:193], v[194:195]
	v_mfma_f32_32x32x16_bf16 v[64:79], v[152:155], v[140:143], v[64:79]
	v_add_f32_e64 v128, v136, v128
	v_add_f32_e64 v129, v137, v129
	v_add_f32_e64 v136, v180, v186
	v_add_f32_e64 v137, v181, v187
	v_add_f32_e64 v130, v136, v130
	v_add_f32_e64 v131, v137, v131
	v_pk_add_f32 v[136:137], v[196:197], v[198:199]
	s_nop 0
	v_pk_add_f32 v[128:129], v[136:137], v[128:129]
	v_pk_add_f32 v[136:137], v[184:185], v[190:191]
	v_mfma_f32_32x32x16_bf16 v[0:15], v[132:135], v[140:143], v[0:15]
	v_add_f32_e64 v130, v136, v130
	v_add_f32_e64 v131, v137, v131
	v_add_f32_e64 v136, v144, v146
	v_add_f32_e64 v137, v145, v147
	v_add_f32_e64 v128, v128, v130
	v_add_f32_e64 v129, v129, v131
	v_pk_add_f32 v[130:131], v[228:229], v[230:231]
	v_pk_add_f32 v[136:137], v[136:137], 0 op_sel_hi:[1,0]
	v_pk_add_f32 v[130:131], v[130:131], 0 op_sel_hi:[1,0]
	v_pk_add_f32 v[128:129], v[166:167], v[128:129]
	v_mfma_f32_32x32x16_bf16 v[80:95], v[152:155], v[208:211], v[80:95]
	v_add_f32_e64 v130, v138, v130
	v_add_f32_e64 v131, v139, v131
	v_add_f32_e64 v138, v234, v238
	v_add_f32_e64 v139, v235, v239
	v_add_f32_e64 v136, v138, v136
	v_add_f32_e64 v137, v139, v137
	v_pk_add_f32 v[138:139], v[240:241], v[244:245]
	s_nop 0
	v_pk_add_f32 v[130:131], v[138:139], v[130:131]
	v_mfma_f32_32x32x16_bf16 v[16:31], v[132:135], v[208:211], v[16:31]
	v_add_f32_e64 v138, v242, v246
	v_add_f32_e64 v139, v243, v247
	v_add_f32_e64 v136, v138, v136
	v_add_f32_e64 v137, v139, v137
	v_add_f32_e64 v138, v248, v206
	v_add_f32_e64 v139, v249, v207
	v_pk_add_f32 v[130:131], v[138:139], v[130:131]
	v_pk_add_f32 v[138:139], v[250:251], v[162:163]
	v_mfma_f32_32x32x16_bf16 v[96:111], v[152:155], v[216:219], v[96:111]
	v_add_f32_e64 v136, v138, v136
	v_add_f32_e64 v137, v139, v137
	v_add_f32_e64 v130, v130, v136
	v_add_f32_e64 v131, v131, v137
	v_add_f32_e64 v166, v128, v130
	v_add_f32_e64 v167, v129, v131
	v_mfma_f32_32x32x16_bf16 v[32:47], v[132:135], v[216:219], v[32:47]
	s_waitcnt lgkmcnt(0)
	v_mfma_f32_32x32x16_bf16 v[112:127], v[152:155], v[224:227], v[112:127]
	v_mfma_f32_32x32x16_bf16 v[48:63], v[132:135], v[224:227], v[48:63]
	s_waitcnt vmcnt(0)
	s_waitcnt lgkmcnt(0)
	s_addk_i32 s5, 0x4000
	s_add_i32 s4, s4, 0x10000
	s_cmp_eq_u32 s4, 0x400000
	s_barrier
	s_cbranch_scc1 .LBB0_410
.LBB0_408:
	s_cmp_eq_u32 s4, 0x3f0000
	s_movk_i32 s7, 0x4000
	s_cbranch_scc1 .LBB0_407
	s_and_b32 s7, s5, 0x4000
	s_branch .LBB0_407
